# m1/m3: wave 0 (extra gate preamble, critical path to barrier 1) runs its preamble at raised issue priority
# baseline (speedup 1.0000x reference)
.LBB0_288:
	s_ashr_i32 s4, s26, 10
	s_and_b32 s28, s26, 0x7f
	s_ashr_i32 s5, s4, 31
	v_mov_b32_e32 v15, v194
	s_lshl_b64 s[20:21], s[4:5], 13
	s_lshl_b32 s4, s28, 6
	s_bfe_u32 s29, s26, 0x30007
	v_and_b32_e32 v14, 63, v15
	v_readfirstlane_b32 s27, v15
	s_or_b32 s20, s20, s4
	v_lshrrev_b32_e32 v209, 3, v15
	v_and_b32_e32 v210, 7, v15
	v_lshlrev_b32_e32 v211, 4, v210
	v_lshl_or_b32 v190, v209, 15, v211
	v_lshl_or_b32 v192, v209, 11, v211
	v_add_u32_e32 v193, 0x1000, v192
	v_lshlrev_b32_e32 v208, 5, v210
	s_lshl_b32 s90, s29, 7
	s_or_b32 s90, s90, 0x400
	s_lshl_b64 s[52:53], s[20:21], 1
	s_add_u32 s52, s22, s52
	s_addc_u32 s53, s23, s53
	s_lshl_b32 s91, s90, 15
	s_add_u32 s52, s52, s91
	s_addc_u32 s53, s53, 0
	s_add_u32 s54, s52, 0x200000
	s_addc_u32 s55, s53, 0
	global_load_dwordx4 v[44:47], v190, s[52:53]
	global_load_dwordx4 v[48:51], v190, s[54:55]
	s_lshl_b32 s91, s29, 8
	s_add_u32 s94, s8, s91
	s_addc_u32 s95, s9, 0
	global_load_dwordx4 v[72:75], v208, s[94:95] offset:2048
	global_load_dwordx4 v[76:79], v208, s[94:95] offset:2064
	s_add_u32 s94, s2, s91
	s_addc_u32 s95, s3, 0
	global_load_dwordx4 v[84:87], v208, s[94:95] offset:2048
	global_load_dwordx4 v[88:91], v208, s[94:95] offset:2064
	s_add_u32 s94, s94, 0x1000
	s_addc_u32 s95, s95, 0
	global_load_dwordx4 v[96:99], v208, s[94:95] offset:2048
	global_load_dwordx4 v[100:103], v208, s[94:95] offset:2064
	s_add_u32 s94, s94, 0x1000
	s_addc_u32 s95, s95, 0
	global_load_dwordx4 v[108:111], v208, s[94:95] offset:2048
	global_load_dwordx4 v[112:115], v208, s[94:95] offset:2064
	s_add_u32 s94, s94, 0x1000
	s_addc_u32 s95, s95, 0
	global_load_dwordx4 v[120:123], v208, s[94:95] offset:2048
	global_load_dwordx4 v[124:127], v208, s[94:95] offset:2064
	s_sub_u32 s92, s20, 3
	s_subb_u32 s93, s21, 0
	s_lshl_b64 s[92:93], s[92:93], 11
	s_add_u32 s92, s0, s92
	s_addc_u32 s93, s1, s93
	s_lshl_b32 s91, s29, 7
	s_add_u32 s92, s92, s91
	s_addc_u32 s93, s93, 0
	s_cmp_lg_u32 s28, 0
	s_cselect_b64 s[54:55], -1, 0
	v_cmp_lt_u32_e32 vcc, 2, v209
	s_or_b64 s[46:47], s[54:55], vcc
	v_cmp_lt_u32_e32 vcc, 1, v209
	s_or_b64 s[48:49], s[54:55], vcc
	v_cmp_lt_u32_e32 vcc, 0, v209
	s_or_b64 s[50:51], s[54:55], vcc
	s_mov_b64 s[96:97], exec
	s_and_b64 exec, s[96:97], s[46:47]
	global_load_dwordx4 v[80:83], v192, s[92:93] offset:1024
	s_and_b64 exec, s[96:97], s[48:49]
	global_load_dwordx4 v[92:95], v192, s[92:93] offset:3072
	s_and_b64 exec, s[96:97], s[50:51]
	global_load_dwordx4 v[104:107], v193, s[92:93] offset:1024
	s_mov_b64 exec, s[96:97]
	global_load_dwordx4 v[116:119], v193, s[92:93] offset:3072
	s_cmp_gt_u32 s27, 63
	v_cmp_gt_u32_e32 vcc, 16, v14
	s_cbranch_scc1 .LBB0_292
	s_setprio 2
	v_or_b32_e32 v0, s20, v14
	v_mov_b32_e32 v1, s21
	v_lshlrev_b64 v[0:1], 6, v[0:1]
	v_lshl_add_u64 v[0:1], s[14:15], 0, v[0:1]
	s_lshl_b32 s86, s29, 2
	v_lshl_add_u64 v[0:1], v[0:1], 0, s[86:87]
	v_mov_b32_e32 v3, s86
	global_load_dword v2, v[0:1], off offset:32
	global_load_dword v4, v3, s[10:11]
	s_nop 0
	global_load_dword v0, v[0:1], off
	s_nop 0
	global_load_dword v1, v3, s[12:13]
	s_waitcnt vmcnt(2)
	v_add_f32_e32 v2, v2, v4
	s_waitcnt vmcnt(0)
	v_add_f32_e32 v0, v0, v1
	v_min_f32_e32 v1, 0, v2
	v_mul_f32_e64 v2, |v2|, s79
	v_exp_f32_e32 v4, v2
	s_nop 0
	v_add_f32_e32 v5, 1.0, v4
	v_add_f32_e32 v2, -1.0, v5
	v_sub_f32_e32 v3, v2, v5
	v_add_f32_e32 v3, 1.0, v3
	v_sub_f32_e32 v2, v4, v2
	v_add_f32_e32 v6, v2, v3
	v_frexp_mant_f32_e32 v2, v5
	v_cmp_gt_f32_e64 s[4:5], s85, v2
	v_cvt_f64_f32_e32 v[2:3], v5
	v_frexp_exp_i32_f64_e32 v2, v[2:3]
	v_subbrev_co_u32_e64 v2, s[4:5], 0, v2, s[4:5]
	v_sub_u32_e32 v3, 0, v2
	v_ldexp_f32 v5, v5, v3
	v_ldexp_f32 v3, v6, v3
	v_add_f32_e32 v6, -1.0, v5
	v_add_f32_e32 v7, 1.0, v6
	v_sub_f32_e32 v7, v5, v7
	v_add_f32_e32 v7, v3, v7
	v_add_f32_e32 v8, v6, v7
	v_sub_f32_e32 v6, v8, v6
	v_sub_f32_e32 v6, v7, v6
	v_add_f32_e32 v7, 1.0, v5
	v_add_f32_e32 v9, -1.0, v7
	v_sub_f32_e32 v5, v5, v9
	v_add_f32_e32 v3, v3, v5
	v_add_f32_e32 v5, v7, v3
	v_sub_f32_e32 v7, v5, v7
	v_sub_f32_e32 v3, v3, v7
	v_rcp_f32_e32 v7, v5
	v_cvt_f32_i32_e32 v2, v2
	s_mov_b32 s4, 0x3f317218
	v_mul_f32_e32 v9, v8, v7
	v_mul_f32_e32 v10, v5, v9
	v_fma_f32 v11, v9, v5, -v10
	v_fmac_f32_e32 v11, v9, v3
	v_add_f32_e32 v12, v10, v11
	v_sub_f32_e32 v13, v8, v12
	v_sub_f32_e32 v8, v8, v13
	v_sub_f32_e32 v10, v12, v10
	v_sub_f32_e32 v8, v8, v12
	v_add_f32_e32 v6, v6, v8
	v_sub_f32_e32 v8, v10, v11
	v_add_f32_e32 v6, v8, v6
	v_add_f32_e32 v8, v13, v6
	v_mul_f32_e32 v10, v7, v8
	v_mul_f32_e32 v11, v5, v10
	v_fma_f32 v5, v10, v5, -v11
	v_fmac_f32_e32 v5, v10, v3
	v_sub_f32_e32 v3, v13, v8
	v_add_f32_e32 v3, v6, v3
	v_add_f32_e32 v6, v11, v5
	v_sub_f32_e32 v12, v8, v6
	v_sub_f32_e32 v8, v8, v12
	v_sub_f32_e32 v11, v6, v11
	v_sub_f32_e32 v6, v8, v6
	v_add_f32_e32 v3, v3, v6
	v_sub_f32_e32 v5, v11, v5
	v_add_f32_e32 v3, v5, v3
	v_add_f32_e32 v5, v9, v10
	v_add_f32_e32 v3, v12, v3
	v_sub_f32_e32 v6, v5, v9
	v_mul_f32_e32 v3, v7, v3
	v_sub_f32_e32 v6, v10, v6
	v_add_f32_e32 v3, v6, v3
	v_mul_f32_e32 v9, 0x3f317218, v2
	v_add_f32_e32 v6, v5, v3
	v_fma_f32 v10, v2, s4, -v9
	v_mul_f32_e32 v7, v6, v6
	v_fmac_f32_e32 v10, 0xb102e308, v2
	v_sub_f32_e32 v2, v6, v5
	v_fmamk_f32 v8, v7, 0x3e9b6dac, v200
	v_sub_f32_e32 v2, v3, v2
	v_add_f32_e32 v3, v9, v10
	v_fmaak_f32 v8, v7, v8, 0x3f2aaada
	v_sub_f32_e32 v5, v3, v9
	v_ldexp_f32 v9, v6, 1
	v_mul_f32_e32 v6, v6, v7
	v_mul_f32_e32 v6, v6, v8
	v_add_f32_e32 v7, v9, v6
	v_sub_f32_e32 v8, v7, v9
	v_ldexp_f32 v2, v2, 1
	v_sub_f32_e32 v6, v6, v8
	v_add_f32_e32 v2, v2, v6
	v_add_f32_e32 v6, v7, v2
	v_sub_f32_e32 v7, v6, v7
	v_sub_f32_e32 v2, v2, v7
	v_add_f32_e32 v7, v3, v6
	v_sub_f32_e32 v8, v7, v3
	v_sub_f32_e32 v9, v7, v8
	v_sub_f32_e32 v5, v10, v5
	v_sub_f32_e32 v3, v3, v9
	v_sub_f32_e32 v6, v6, v8
	v_add_f32_e32 v3, v6, v3
	v_add_f32_e32 v6, v5, v2
	v_sub_f32_e32 v8, v6, v5
	v_sub_f32_e32 v9, v6, v8
	v_sub_f32_e32 v5, v5, v9
	v_sub_f32_e32 v2, v2, v8
	v_add_f32_e32 v3, v6, v3
	v_add_f32_e32 v2, v2, v5
	v_add_f32_e32 v5, v7, v3
	v_sub_f32_e32 v6, v5, v7
	v_sub_f32_e32 v3, v3, v6
	v_add_f32_e32 v2, v2, v3
	s_mov_b32 s4, 0x7f800000
	v_add_f32_e32 v2, v5, v2
	v_cmp_neq_f32_e64 s[4:5], s4, v4
	v_add_u32_e32 v3, -1, v201
	s_nop 0
	v_cndmask_b32_e64 v2, v202, v2, s[4:5]
	v_cmp_ngt_f32_e64 s[4:5], -1.0, v4
	s_nop 1
	v_cndmask_b32_e64 v2, v203, v2, s[4:5]
	v_cmp_neq_f32_e64 s[4:5], -1.0, v4
	s_nop 1
	v_cndmask_b32_e64 v2, v204, v2, s[4:5]
	s_mov_b32 s4, 0x33800000
	v_cmp_lt_f32_e64 s[4:5], |v4|, s4
	s_nop 1
	v_cndmask_b32_e64 v2, v2, v4, s[4:5]
	v_sub_f32_e32 v1, v1, v2
	v_mov_b32_e32 v4, v1
	s_nop 1
	v_add_f32_dpp v4, v1, v4 row_shr:1 row_mask:0xf bank_mask:0xf
	v_add_f32_dpp v4, v1, v4 row_shr:2 row_mask:0xf bank_mask:0xf
	v_add_f32_dpp v4, v1, v4 row_shr:3 row_mask:0xf bank_mask:0xf
	s_nop 1
	v_add_f32_dpp v4, v4, v4 row_shr:4 row_mask:0xf bank_mask:0xe
	s_nop 1
	v_add_f32_dpp v4, v4, v4 row_shr:8 row_mask:0xf bank_mask:0xc
	s_nop 1
	v_add_f32_dpp v4, v4, v4 row_bcast:15 row_mask:0xa bank_mask:0xf
	s_nop 1
	v_add_f32_dpp v4, v4, v4 row_bcast:31 row_mask:0xc bank_mask:0xf
	s_nop 0
	v_readlane_b32 s6, v4, 63
	s_nop 1
	v_mov_b32_e32 v1, s6
	v_sub_f32_e32 v2, v1, v4
	v_add_f32_e32 v2, v0, v2
	v_mov_b32_e32 v3, v2
	s_nop 1
	v_max_f32_dpp v3, v2, v3 row_shr:1 row_mask:0xf bank_mask:0xf
	v_max_f32_dpp v3, v2, v3 row_shr:2 row_mask:0xf bank_mask:0xf
	v_max_f32_dpp v3, v2, v3 row_shr:3 row_mask:0xf bank_mask:0xf
	s_nop 1
	v_max_f32_dpp v3, v3, v3 row_shr:4 row_mask:0xf bank_mask:0xe
	s_nop 1
	v_max_f32_dpp v3, v3, v3 row_shr:8 row_mask:0xf bank_mask:0xc
	s_nop 1
	v_max_f32_dpp v3, v3, v3 row_bcast:15 row_mask:0xa bank_mask:0xf
	s_nop 1
	v_max_f32_dpp v3, v3, v3 row_bcast:31 row_mask:0xc bank_mask:0xf
	s_nop 0
	v_readlane_b32 s7, v3, 63
	v_cmp_eq_u32_e64 s[4:5], 0, v14
	s_nop 1
	v_mov_b32_e32 v0, s7
	v_sub_f32_e32 v2, v2, v0
	v_mul_f32_e32 v2, 0x3fb8aa3b, v2
	v_exp_f32_e32 v2, v2
	v_lshl_add_u32 v3, v14, 2, 0
	ds_write_b32 v3, v2 offset:29952
	s_and_saveexec_b64 s[6:7], s[4:5]
	s_cbranch_execz .LBB0_291
	s_ashr_i32 s19, s18, 31
	s_lshl_b64 s[4:5], s[18:19], 2
	s_add_u32 s4, s24, s4
	s_addc_u32 s5, s25, s5
	global_store_dwordx2 v172, v[0:1], s[4:5]
.LBB0_291:
	s_or_b64 exec, exec, s[6:7]
	s_setprio 0

.LBB0_449:
	s_ashr_i32 s2, s39, 10
	s_and_b32 s41, s39, 0x7f
	s_ashr_i32 s3, s2, 31
	v_mov_b32_e32 v23, v194
	s_lshl_b64 s[34:35], s[2:3], 13
	s_lshl_b32 s2, s41, 6
	s_bfe_u32 s42, s39, 0x30007
	v_readfirstlane_b32 s40, v23
	s_or_b32 s34, s34, s2
	v_lshrrev_b32_e32 v209, 3, v23
	v_and_b32_e32 v210, 7, v23
	v_lshlrev_b32_e32 v211, 4, v210
	v_lshl_or_b32 v190, v209, 15, v211
	v_lshlrev_b32_e32 v191, 4, v23
	v_lshl_or_b32 v192, v209, 11, v211
	v_add_u32_e32 v193, 0x1000, v192
	v_lshlrev_b32_e32 v208, 5, v210
	s_lshl_b32 s90, s42, 7
	s_or_b32 s90, s90, 0x400
	s_lshl_b64 s[52:53], s[34:35], 1
	s_add_u32 s52, s33, s52
	s_addc_u32 s53, s36, s53
	s_lshl_b32 s91, s90, 15
	s_add_u32 s52, s52, s91
	s_addc_u32 s53, s53, 0
	s_add_u32 s54, s52, 0x200000
	s_addc_u32 s55, s53, 0
	global_load_dwordx4 v[44:47], v190, s[52:53]
	global_load_dwordx4 v[48:51], v190, s[54:55]
	s_mul_i32 s92, s39, 0x4080
	s_mul_hi_i32 s93, s39, 0x4080
	s_add_u32 s92, s37, s92
	s_addc_u32 s93, s38, s93
	global_load_dwordx4 v[52:55], v191, s[92:93]
	s_add_u32 s94, s92, 0x2000
	s_addc_u32 s95, s93, 0
	global_load_dwordx4 v[56:59], v191, s[94:95]
	s_add_u32 s94, s92, 0x4000
	s_addc_u32 s95, s93, 0
	v_cmp_gt_u32_e32 vcc, 8, v23
	s_and_saveexec_b64 s[96:97], vcc
	global_load_dwordx4 v[60:63], v191, s[94:95]
	s_mov_b64 exec, s[96:97]
	s_lshl_b32 s91, s42, 8
	s_add_u32 s94, s18, s91
	s_addc_u32 s95, s19, 0
	global_load_dwordx4 v[64:67], v208, s[94:95]
	global_load_dwordx4 v[68:71], v208, s[94:95] offset:16
	global_load_dwordx4 v[72:75], v208, s[94:95] offset:2048
	global_load_dwordx4 v[76:79], v208, s[94:95] offset:2064
	s_add_u32 s94, s16, s91
	s_addc_u32 s95, s17, 0
	global_load_dwordx4 v[84:87], v208, s[94:95]
	global_load_dwordx4 v[88:91], v208, s[94:95] offset:16
	global_load_dwordx4 v[132:135], v208, s[94:95] offset:2048
	global_load_dwordx4 v[136:139], v208, s[94:95] offset:2064
	s_add_u32 s94, s94, 0x1000
	s_addc_u32 s95, s95, 0
	global_load_dwordx4 v[96:99], v208, s[94:95]
	global_load_dwordx4 v[100:103], v208, s[94:95] offset:16
	global_load_dwordx4 v[144:147], v208, s[94:95] offset:2048
	global_load_dwordx4 v[148:151], v208, s[94:95] offset:2064
	s_add_u32 s94, s94, 0x1000
	s_addc_u32 s95, s95, 0
	global_load_dwordx4 v[108:111], v208, s[94:95]
	global_load_dwordx4 v[112:115], v208, s[94:95] offset:16
	global_load_dwordx4 v[156:159], v208, s[94:95] offset:2048
	global_load_dwordx4 v[160:163], v208, s[94:95] offset:2064
	s_add_u32 s94, s94, 0x1000
	s_addc_u32 s95, s95, 0
	global_load_dwordx4 v[120:123], v208, s[94:95]
	global_load_dwordx4 v[124:127], v208, s[94:95] offset:16
	global_load_dwordx4 v[182:185], v208, s[94:95] offset:2048
	global_load_dwordx4 v[186:189], v208, s[94:95] offset:2064
	s_sub_u32 s92, s34, 3
	s_subb_u32 s93, s35, 0
	s_lshl_b64 s[92:93], s[92:93], 11
	s_add_u32 s92, s14, s92
	s_addc_u32 s93, s15, s93
	s_lshl_b32 s91, s42, 7
	s_add_u32 s92, s92, s91
	s_addc_u32 s93, s93, 0
	s_cmp_lg_u32 s41, 0
	s_cselect_b64 s[54:55], -1, 0
	v_cmp_lt_u32_e32 vcc, 2, v209
	s_or_b64 s[46:47], s[54:55], vcc
	v_cmp_lt_u32_e32 vcc, 1, v209
	s_or_b64 s[48:49], s[54:55], vcc
	v_cmp_lt_u32_e32 vcc, 0, v209
	s_or_b64 s[50:51], s[54:55], vcc
	s_mov_b64 s[96:97], exec
	s_and_b64 exec, s[96:97], s[46:47]
	global_load_dwordx4 v[80:83], v192, s[92:93]
	global_load_dwordx4 v[128:131], v192, s[92:93] offset:1024
	s_and_b64 exec, s[96:97], s[48:49]
	global_load_dwordx4 v[92:95], v192, s[92:93] offset:2048
	global_load_dwordx4 v[140:143], v192, s[92:93] offset:3072
	s_and_b64 exec, s[96:97], s[50:51]
	global_load_dwordx4 v[104:107], v193, s[92:93]
	global_load_dwordx4 v[152:155], v193, s[92:93] offset:1024
	s_mov_b64 exec, s[96:97]
	global_load_dwordx4 v[116:119], v193, s[92:93] offset:2048
	global_load_dwordx4 v[178:181], v193, s[92:93] offset:3072
	s_lshr_b32 s90, s40, 6
	s_lshl_b32 s90, s90, 3
	s_add_u32 s90, s34, s90
	s_addc_u32 s91, s35, 0
	s_lshl_b64 s[90:91], s[90:91], 11
	s_add_u32 s90, s22, s90
	s_addc_u32 s91, s23, s91
	s_lshl_b32 s92, s42, 8
	v_and_b32_e32 v232, 63, v23
	v_lshlrev_b32_e32 v233, 3, v232
	v_lshl_or_b32 v232, v232, 2, s92
	global_load_dword v224, v232, s[90:91]
	global_load_dword v225, v232, s[90:91] offset:2048
	s_add_u32 s90, s90, 0x1000
	s_addc_u32 s91, s91, 0
	global_load_dword v226, v232, s[90:91]
	global_load_dword v227, v232, s[90:91] offset:2048
	s_add_u32 s90, s90, 0x1000
	s_addc_u32 s91, s91, 0
	global_load_dword v228, v232, s[90:91]
	global_load_dword v229, v232, s[90:91] offset:2048
	s_add_u32 s90, s90, 0x1000
	s_addc_u32 s91, s91, 0
	global_load_dword v230, v232, s[90:91]
	global_load_dword v231, v232, s[90:91] offset:2048
	global_load_dwordx2 v[234:235], v233, s[20:21]
	s_cmp_gt_u32 s40, 63
	v_and_b32_e32 v22, 63, v23
	s_cbranch_scc1 .LBB0_451
	s_setprio 2
	v_or_b32_e32 v0, s34, v22
	v_mov_b32_e32 v1, s35
	v_lshlrev_b64 v[0:1], 6, v[0:1]
	v_lshl_add_u64 v[0:1], s[30:31], 0, v[0:1]
	s_lshl_b32 s86, s42, 2
	v_lshl_add_u64 v[0:1], v[0:1], 0, s[86:87]
	v_mov_b32_e32 v3, s86
	global_load_dword v2, v[0:1], off offset:32
	global_load_dword v4, v3, s[26:27]
	s_nop 0
	global_load_dword v0, v[0:1], off
	s_nop 0
	global_load_dword v1, v3, s[28:29]
	s_lshl_b32 s98, s39, 4
	s_add_u32 s98, s0, s98
	s_addc_u32 s99, s1, 0
	v_mov_b32_e32 v41, 0x18100000
	global_load_dword v42, v41, s[98:99] offset:8
	s_mov_b32 s2, 0x3f317218
	s_waitcnt vmcnt(2)
	v_add_f32_e32 v2, v2, v4
	s_waitcnt vmcnt(0)
	v_add_f32_e32 v1, v0, v1
	v_min_f32_e32 v0, 0, v2
	v_mul_f32_e64 v2, |v2|, s79
	v_exp_f32_e32 v4, v2
	s_nop 0
	v_add_f32_e32 v5, 1.0, v4
	v_add_f32_e32 v2, -1.0, v5
	v_sub_f32_e32 v3, v2, v5
	v_add_f32_e32 v3, 1.0, v3
	v_sub_f32_e32 v2, v4, v2
	v_add_f32_e32 v6, v2, v3
	v_frexp_mant_f32_e32 v2, v5
	v_cmp_gt_f32_e32 vcc, s85, v2
	v_cvt_f64_f32_e32 v[2:3], v5
	v_frexp_exp_i32_f64_e32 v2, v[2:3]
	v_subbrev_co_u32_e32 v2, vcc, 0, v2, vcc
	v_sub_u32_e32 v3, 0, v2
	v_ldexp_f32 v5, v5, v3
	v_ldexp_f32 v3, v6, v3
	v_add_f32_e32 v6, -1.0, v5
	v_add_f32_e32 v7, 1.0, v6
	v_sub_f32_e32 v7, v5, v7
	v_add_f32_e32 v7, v3, v7
	v_add_f32_e32 v8, v6, v7
	v_sub_f32_e32 v6, v8, v6
	v_sub_f32_e32 v6, v7, v6
	v_add_f32_e32 v7, 1.0, v5
	v_add_f32_e32 v9, -1.0, v7
	v_sub_f32_e32 v5, v5, v9
	v_add_f32_e32 v3, v3, v5
	v_add_f32_e32 v5, v7, v3
	v_sub_f32_e32 v7, v5, v7
	v_sub_f32_e32 v3, v3, v7
	v_rcp_f32_e32 v7, v5
	v_cvt_f32_i32_e32 v2, v2
	v_mul_f32_e32 v9, v8, v7
	v_mul_f32_e32 v10, v5, v9
	v_fma_f32 v11, v9, v5, -v10
	v_fmac_f32_e32 v11, v9, v3
	v_add_f32_e32 v12, v10, v11
	v_sub_f32_e32 v13, v8, v12
	v_sub_f32_e32 v8, v8, v13
	v_sub_f32_e32 v10, v12, v10
	v_sub_f32_e32 v8, v8, v12
	v_add_f32_e32 v6, v6, v8
	v_sub_f32_e32 v8, v10, v11
	v_add_f32_e32 v6, v8, v6
	v_add_f32_e32 v8, v13, v6
	v_mul_f32_e32 v10, v7, v8
	v_mul_f32_e32 v11, v5, v10
	v_fma_f32 v5, v10, v5, -v11
	v_fmac_f32_e32 v5, v10, v3
	v_sub_f32_e32 v3, v13, v8
	v_add_f32_e32 v3, v6, v3
	v_add_f32_e32 v6, v11, v5
	v_sub_f32_e32 v12, v8, v6
	v_sub_f32_e32 v8, v8, v12
	v_sub_f32_e32 v11, v6, v11
	v_sub_f32_e32 v6, v8, v6
	v_add_f32_e32 v3, v3, v6
	v_sub_f32_e32 v5, v11, v5
	v_add_f32_e32 v3, v5, v3
	v_add_f32_e32 v5, v9, v10
	v_add_f32_e32 v3, v12, v3
	v_sub_f32_e32 v6, v5, v9
	v_mul_f32_e32 v3, v7, v3
	v_sub_f32_e32 v6, v10, v6
	v_add_f32_e32 v3, v6, v3
	v_mul_f32_e32 v9, 0x3f317218, v2
	v_add_f32_e32 v6, v5, v3
	v_fma_f32 v10, v2, s2, -v9
	v_mul_f32_e32 v7, v6, v6
	v_fmac_f32_e32 v10, 0xb102e308, v2
	v_sub_f32_e32 v2, v6, v5
	v_fmamk_f32 v8, v7, 0x3e9b6dac, v200
	v_sub_f32_e32 v2, v3, v2
	v_add_f32_e32 v3, v9, v10
	v_fmaak_f32 v8, v7, v8, 0x3f2aaada
	v_sub_f32_e32 v5, v3, v9
	v_ldexp_f32 v9, v6, 1
	v_mul_f32_e32 v6, v6, v7
	v_mul_f32_e32 v6, v6, v8
	v_add_f32_e32 v7, v9, v6
	v_sub_f32_e32 v8, v7, v9
	v_ldexp_f32 v2, v2, 1
	v_sub_f32_e32 v6, v6, v8
	v_add_f32_e32 v2, v2, v6
	v_add_f32_e32 v6, v7, v2
	v_sub_f32_e32 v7, v6, v7
	v_sub_f32_e32 v2, v2, v7
	v_add_f32_e32 v7, v3, v6
	v_sub_f32_e32 v8, v7, v3
	v_sub_f32_e32 v9, v7, v8
	v_sub_f32_e32 v5, v10, v5
	v_sub_f32_e32 v3, v3, v9
	v_sub_f32_e32 v6, v6, v8
	v_add_f32_e32 v3, v6, v3
	v_add_f32_e32 v6, v5, v2
	v_sub_f32_e32 v8, v6, v5
	v_sub_f32_e32 v9, v6, v8
	v_sub_f32_e32 v5, v5, v9
	v_sub_f32_e32 v2, v2, v8
	v_add_f32_e32 v3, v6, v3
	v_add_f32_e32 v2, v2, v5
	v_add_f32_e32 v5, v7, v3
	v_sub_f32_e32 v6, v5, v7
	v_sub_f32_e32 v3, v3, v6
	v_add_f32_e32 v2, v2, v3
	s_mov_b32 s2, 0x7f800000
	v_add_f32_e32 v2, v5, v2
	v_cmp_neq_f32_e32 vcc, s2, v4
	s_mov_b32 s2, 0x33800000
	v_add_u32_e32 v3, -1, v201
	v_cndmask_b32_e32 v2, v202, v2, vcc
	v_cmp_ngt_f32_e32 vcc, -1.0, v4
	s_nop 1
	v_cndmask_b32_e32 v2, v203, v2, vcc
	v_cmp_neq_f32_e32 vcc, -1.0, v4
	s_nop 1
	v_cndmask_b32_e32 v2, v204, v2, vcc
	v_cmp_lt_f32_e64 vcc, |v4|, s2
	s_lshl_b32 s2, s39, 2
	s_ashr_i32 s3, s2, 31
	v_cndmask_b32_e32 v2, v2, v4, vcc
	v_sub_f32_e32 v0, v0, v2
	v_mov_b32_e32 v4, v0
	s_nop 1
	v_add_f32_dpp v4, v0, v4 row_shr:1 row_mask:0xf bank_mask:0xf
	v_add_f32_dpp v4, v0, v4 row_shr:2 row_mask:0xf bank_mask:0xf
	v_add_f32_dpp v4, v0, v4 row_shr:3 row_mask:0xf bank_mask:0xf
	s_nop 1
	v_add_f32_dpp v4, v4, v4 row_shr:4 row_mask:0xf bank_mask:0xe
	s_nop 1
	v_add_f32_dpp v4, v4, v4 row_shr:8 row_mask:0xf bank_mask:0xc
	s_nop 1
	v_add_f32_dpp v4, v4, v4 row_bcast:15 row_mask:0xa bank_mask:0xf
	s_nop 1
	v_add_f32_dpp v4, v4, v4 row_bcast:31 row_mask:0xc bank_mask:0xf
	v_mov_b32_e32 v0, v4
	v_sub_f32_e32 v1, v1, v0
	v_mov_b32_e32 v3, v1
	s_nop 1
	v_max_f32_dpp v3, v1, v3 row_shr:1 row_mask:0xf bank_mask:0xf
	v_max_f32_dpp v3, v1, v3 row_shr:2 row_mask:0xf bank_mask:0xf
	v_max_f32_dpp v3, v1, v3 row_shr:3 row_mask:0xf bank_mask:0xf
	s_nop 1
	v_max_f32_dpp v3, v3, v3 row_shr:4 row_mask:0xf bank_mask:0xe
	s_nop 1
	v_max_f32_dpp v3, v3, v3 row_shr:8 row_mask:0xf bank_mask:0xc
	s_nop 1
	v_max_f32_dpp v3, v3, v3 row_bcast:15 row_mask:0xa bank_mask:0xf
	s_nop 1
	v_max_f32_dpp v3, v3, v3 row_bcast:31 row_mask:0xc bank_mask:0xf
	v_mov_b32_e32 v2, v3
	v_max_f32_e32 v2, v2, v2
	s_waitcnt vmcnt(0)
	v_mov_b32_e32 v3, v42
	v_max_f32_e32 v4, v3, v3
	v_max_f32_e32 v2, v4, v2
	v_lshl_add_u32 v4, v22, 2, 0
	v_add_u32_e32 v4, 0x19200, v4
	ds_write2st64_b32 v4, v1, v2 offset1:1
	v_sub_f32_e32 v1, v3, v2
	v_add_f32_e32 v0, v0, v2
	v_mul_f32_e32 v1, 0x3fb8aa3b, v1
	v_mul_f32_e32 v0, 0xbfb8aa3b, v0
	v_exp_f32_e32 v1, v1
	v_exp_f32_e32 v0, v0
	ds_write2st64_b32 v4, v1, v0 offset0:2 offset1:3
	s_setprio 0
